# v47 + waves 4-7 run their post-barrier MFMA block at priority 2
# baseline (speedup 1.0000x reference)
; DI void expsum(f32x16& p, float& l_reg, bf16x8& pa0, bf16x8& pa1) {
; #pragma unroll
;     for (int r = 0; r < 16; ++r) p[r] = __builtin_amdgcn_exp2f(p[r]);
;     float ps = 0.f;
; #pragma unroll
;     for (int r = 0; r < 16; ++r) ps += p[r];
;     l_reg += ps; asm volatile("" : "+v"(l_reg));
;     ...
;     ATT_PK4(p, 0, pa0); ATT_PK4(p, 8, pa1);
;     ...
; }
; DI int v_rd_base(int lane) { return ((lane & 3) << 3) | (((lane >> 2) & 3) << 6) | (((lane >> 4) & 1) << 5) | (((lane >> 5) & 1) << 8); }
; template <int OFF> DI s16x4 tr_read(int vb) { s16x4 r; asm volatile("ds_read_b64_tr_b16 %0, %1 offset:%2" : "=&v"(r) : "v"(vb), "i"(OFF) : "memory"); return r; }
; template <int H> DI void v_reads(s16x4* vf, int vb) {
;     vf[0] = tr_read<v_rd_off(0, 2 * H, 0)>(vb); vf[1] = tr_read<v_rd_off(0, 2 * H, 1)>(vb); vf[2] = tr_read<v_rd_off(0, 2 * H + 1, 0)>(vb); vf[3] = tr_read<v_rd_off(0, 2 * H + 1, 1)>(vb);
;     vf[4] = tr_read<v_rd_off(1, 2 * H, 0)>(vb); vf[5] = tr_read<v_rd_off(1, 2 * H, 1)>(vb); vf[6] = tr_read<v_rd_off(1, 2 * H + 1, 0)>(vb); vf[7] = tr_read<v_rd_off(1, 2 * H + 1, 1)>(vb);
;     vf[8] = tr_read<v_rd_off(2, 2 * H, 0)>(vb); vf[9] = tr_read<v_rd_off(2, 2 * H, 1)>(vb); vf[10] = tr_read<v_rd_off(2, 2 * H + 1, 0)>(vb); vf[11] = tr_read<v_rd_off(2, 2 * H + 1, 1)>(vb);
;     vf[12] = tr_read<v_rd_off(3, 2 * H, 0)>(vb); vf[13] = tr_read<v_rd_off(3, 2 * H, 1)>(vb); vf[14] = tr_read<v_rd_off(3, 2 * H + 1, 0)>(vb); vf[15] = tr_read<v_rd_off(3, 2 * H + 1, 1)>(vb);
; }
; template <int DQK, int MODE, int LDQ, int LDK, int LDV> ...
;     ...
;     constexpr int NDA = ND0 > 6 ? 6 : ND0;
.LBB0_1924:
	s_add_i32 s3, s22, 0xffffc000
	s_and_b32 s3, s3, 0x6000
	v_add_u32_e32 v123, s3, v114
	v_add_u32_e32 v140, v123, v118
	v_add_u32_e32 v136, v123, v117
	v_add_u32_e32 v132, v123, v116
	v_add_u32_e32 v123, v123, v115
	ds_read_b128 v[124:127], v123
	ds_read_b128 v[132:135], v132
	ds_read_b128 v[136:139], v136
	ds_read_b128 v[140:143], v140
	ds_read_b64_tr_b16 v[144:145], v121 offset:0x2000
	ds_read_b64_tr_b16 v[146:147], v121 offset:0x2800
	ds_read_b64_tr_b16 v[148:149], v121 offset:0x3000
	ds_read_b64_tr_b16 v[150:151], v121 offset:0x3800
	ds_read_b64_tr_b16 v[152:153], v121 offset:0x2200
	ds_read_b64_tr_b16 v[154:155], v121 offset:0x2a00
	ds_read_b64_tr_b16 v[156:157], v121 offset:0x3200
	ds_read_b64_tr_b16 v[158:159], v121 offset:0x3a00
	ds_read_b64_tr_b16 v[162:163], v121 offset:0x2400
	ds_read_b64_tr_b16 v[164:165], v121 offset:0x2c00
	ds_read_b64_tr_b16 v[166:167], v121 offset:0x3400
	ds_read_b64_tr_b16 v[168:169], v121 offset:0x3c00
	ds_read_b64_tr_b16 v[170:171], v121 offset:0x2600
	ds_read_b64_tr_b16 v[172:173], v121 offset:0x2e00
	ds_read_b64_tr_b16 v[174:175], v121 offset:0x3600
	ds_read_b64_tr_b16 v[176:177], v121 offset:0x3e00
	s_setprio 2
	v_exp_f32_e32 v64, v64
	v_exp_f32_e32 v65, v65
	v_exp_f32_e32 v66, v66
	v_exp_f32_e32 v67, v67
	v_exp_f32_e32 v68, v68
	v_add_f32_e32 v121, 0, v64
	v_exp_f32_e32 v69, v69
	v_add_f32_e32 v121, v65, v121
	v_exp_f32_e32 v70, v70
	v_add_f32_e32 v121, v66, v121
	v_exp_f32_e32 v71, v71
	v_add_f32_e32 v121, v67, v121
	v_exp_f32_e32 v72, v72
	v_add_f32_e32 v121, v68, v121
	v_exp_f32_e32 v73, v73
	v_add_f32_e32 v121, v69, v121
	v_exp_f32_e32 v74, v74
	v_add_f32_e32 v121, v70, v121
	v_exp_f32_e32 v75, v75
	v_add_f32_e32 v121, v71, v121
	v_exp_f32_e32 v76, v76
	v_add_f32_e32 v121, v72, v121
	v_exp_f32_e32 v77, v77
	v_add_f32_e32 v121, v73, v121
	v_exp_f32_e32 v78, v78
	v_add_f32_e32 v121, v74, v121
	v_exp_f32_e32 v79, v79
	v_add_f32_e32 v121, v75, v121
	v_add_f32_e32 v121, v76, v121
	v_add_f32_e32 v121, v77, v121
	v_add_f32_e32 v121, v78, v121
	v_add_f32_e32 v121, v79, v121
	v_add_f32_e32 v120, v120, v121
	v_cvt_pk_bf16_f32 v64, v64, v65
	v_cvt_pk_bf16_f32 v65, v66, v67
	v_cvt_pk_bf16_f32 v66, v68, v69
	v_cvt_pk_bf16_f32 v67, v70, v71
	v_cvt_pk_bf16_f32 v68, v72, v73
	v_cvt_pk_bf16_f32 v69, v74, v75
	v_cvt_pk_bf16_f32 v70, v76, v77
	v_cvt_pk_bf16_f32 v71, v78, v79
	s_nop 0
	v_permlane32_swap_b32_e32 v64, v66
	v_permlane32_swap_b32_e32 v65, v67
	v_permlane32_swap_b32_e32 v68, v70
	v_permlane32_swap_b32_e32 v69, v71
	s_waitcnt lgkmcnt(0)
	s_setprio 1
	s_cmp_lt_u32 s33, 0x100
	s_cbranch_scc1 .Lstg_d0_mid_11
	s_waitcnt vmcnt(3)
	s_barrier
	s_setprio 2

; #define SBAR() __builtin_amdgcn_sched_barrier(0)
; DI void expsum(f32x16& p, float& l_reg, bf16x8& pa0, bf16x8& pa1) {
; #pragma unroll
;     for (int r = 0; r < 16; ++r) p[r] = __builtin_amdgcn_exp2f(p[r]);
;     float ps = 0.f;
; #pragma unroll
;     for (int r = 0; r < 16; ++r) ps += p[r];
;     l_reg += ps; asm volatile("" : "+v"(l_reg));
;     ...
;     ATT_PK4(p, 0, pa0); ATT_PK4(p, 8, pa1);
;     ...
; }
; DI int v_rd_base(int lane) { return ((lane & 3) << 3) | (((lane >> 2) & 3) << 6) | (((lane >> 4) & 1) << 5) | (((lane >> 5) & 1) << 8); }
; template <int OFF> DI s16x4 tr_read(int vb) { s16x4 r; asm volatile("ds_read_b64_tr_b16 %0, %1 offset:%2" : "=&v"(r) : "v"(vb), "i"(OFF) : "memory"); return r; }
; template <int H> DI void v_reads(s16x4* vf, int vb) {
;     vf[0] = tr_read<v_rd_off(0, 2 * H, 0)>(vb); vf[1] = tr_read<v_rd_off(0, 2 * H, 1)>(vb); vf[2] = tr_read<v_rd_off(0, 2 * H + 1, 0)>(vb); vf[3] = tr_read<v_rd_off(0, 2 * H + 1, 1)>(vb);
;     vf[4] = tr_read<v_rd_off(1, 2 * H, 0)>(vb); vf[5] = tr_read<v_rd_off(1, 2 * H, 1)>(vb); vf[6] = tr_read<v_rd_off(1, 2 * H + 1, 0)>(vb); vf[7] = tr_read<v_rd_off(1, 2 * H + 1, 1)>(vb);
;     vf[8] = tr_read<v_rd_off(2, 2 * H, 0)>(vb); vf[9] = tr_read<v_rd_off(2, 2 * H, 1)>(vb); vf[10] = tr_read<v_rd_off(2, 2 * H + 1, 0)>(vb); vf[11] = tr_read<v_rd_off(2, 2 * H + 1, 1)>(vb);
;     vf[12] = tr_read<v_rd_off(3, 2 * H, 0)>(vb); vf[13] = tr_read<v_rd_off(3, 2 * H, 1)>(vb); vf[14] = tr_read<v_rd_off(3, 2 * H + 1, 0)>(vb); vf[15] = tr_read<v_rd_off(3, 2 * H + 1, 1)>(vb);
; }
; template <int DQK, int MODE, int LDQ, int LDK, int LDV> ...
;     ...
;     constexpr int NDA = ND0 > 6 ? 6 : ND0;
;     ...
;     f32x16 pA, pB; bf16x8 pa0, pa1;
;     int v0 = 0, v1 = 1, v2 = 2;
;     ATT_TOP(NKP + 2);
;     { bf16x8 kf[NDA]; k_reads<DQK, 0, NDA>(kf, lds, 0, r32, hi); ATT_LGKM0(); qk_mma<0, NDA>(pA, kf, qr);
;       if constexpr (ND0 > NDA) { bf16x8 kg[ND0 - NDA]; k_reads<DQK, NDA, ND0>(kg, lds, 0, r32, hi); ATT_LGKM0(); qk_mma<NDA, ND0>(pA, kg, qr); }
;       ATT_BIAS(pA, 0, 0); }
;     if (wid >= 4) __builtin_amdgcn_s_setprio(1);
;     for (int j = 0; j < NT; ++j) {
;         if (j + 2 < NT) ATT_TOP(NKP + 2); else ATT_TOP(0);
;         if (j + 3 < NT) ATT_DMA_K(j + 3);
;         if (j + 2 < NT) ATT_DMA_V(j + 2, v2);
;         ATT_SEG(j); SBAR();
;         ATT_STEP(pA, pB, 0, v0, true, 1, j);
;         ATT_STEP(pB, pA, 1, v0, (j + 1 < NT), 0, j + 1);
.LBB0_1932:
	s_movk_i32 s64, 0x70
	ds_read_b128 v[98:101], v107 offset:16384
	ds_read_b128 v[102:105], v108 offset:16384
	ds_read_b128 v[114:117], v109 offset:16384
	ds_read_b128 v[118:121], v110 offset:16384
	ds_read_b64_tr_b16 v[122:123], v96 offset:0x2000
	ds_read_b64_tr_b16 v[124:125], v96 offset:0x2800
	ds_read_b64_tr_b16 v[132:133], v96 offset:0x3000
	ds_read_b64_tr_b16 v[134:135], v96 offset:0x3800
	ds_read_b64_tr_b16 v[136:137], v96 offset:0x2200
	ds_read_b64_tr_b16 v[138:139], v96 offset:0x2a00
	ds_read_b64_tr_b16 v[140:141], v96 offset:0x3200
	ds_read_b64_tr_b16 v[142:143], v96 offset:0x3a00
	ds_read_b64_tr_b16 v[144:145], v96 offset:0x2400
	ds_read_b64_tr_b16 v[146:147], v96 offset:0x2c00
	ds_read_b64_tr_b16 v[148:149], v96 offset:0x3400
	ds_read_b64_tr_b16 v[150:151], v96 offset:0x3c00
	ds_read_b64_tr_b16 v[152:153], v96 offset:0x2600
	ds_read_b64_tr_b16 v[154:155], v96 offset:0x2e00
	ds_read_b64_tr_b16 v[156:157], v96 offset:0x3600
	ds_read_b64_tr_b16 v[158:159], v96 offset:0x3e00
	s_nop 5
	s_setprio 2
	v_exp_f32_e32 v64, v64
	v_exp_f32_e32 v65, v65
	v_exp_f32_e32 v66, v66
	v_exp_f32_e32 v67, v67
	v_exp_f32_e32 v68, v68
	v_add_f32_e32 v96, 0, v64
	v_exp_f32_e32 v69, v69
	v_add_f32_e32 v96, v65, v96
	v_exp_f32_e32 v70, v70
	v_add_f32_e32 v96, v66, v96
	v_exp_f32_e32 v71, v71
	v_add_f32_e32 v96, v67, v96
	v_exp_f32_e32 v72, v72
	v_add_f32_e32 v96, v68, v96
	v_exp_f32_e32 v73, v73
	v_add_f32_e32 v96, v69, v96
	v_exp_f32_e32 v74, v74
	v_add_f32_e32 v96, v70, v96
	v_exp_f32_e32 v75, v75
	v_add_f32_e32 v96, v71, v96
	v_exp_f32_e32 v76, v76
	v_add_f32_e32 v96, v72, v96
	v_exp_f32_e32 v77, v77
	v_add_f32_e32 v96, v73, v96
	v_exp_f32_e32 v78, v78
	v_add_f32_e32 v96, v74, v96
	v_exp_f32_e32 v79, v79
	v_add_f32_e32 v96, v75, v96
	v_add_f32_e32 v96, v76, v96
	v_add_f32_e32 v96, v77, v96
	v_add_f32_e32 v96, v78, v96
	v_add_f32_e32 v96, v79, v96
	v_add_f32_e32 v96, v97, v96
	v_cvt_pk_bf16_f32 v64, v64, v65
	v_cvt_pk_bf16_f32 v65, v66, v67
	v_cvt_pk_bf16_f32 v66, v68, v69
	v_cvt_pk_bf16_f32 v67, v70, v71
	v_cvt_pk_bf16_f32 v68, v72, v73
	v_cvt_pk_bf16_f32 v69, v74, v75
	v_cvt_pk_bf16_f32 v70, v76, v77
	v_cvt_pk_bf16_f32 v71, v78, v79
	s_nop 0
	v_permlane32_swap_b32_e32 v64, v66
	v_permlane32_swap_b32_e32 v65, v67
	v_permlane32_swap_b32_e32 v68, v70
	v_permlane32_swap_b32_e32 v69, v71
	s_waitcnt lgkmcnt(0)
	s_setprio 1
	s_cmp_lt_u32 s33, 0x100
	s_cbranch_scc1 .Lstg_d0_m61_13
	s_waitcnt vmcnt(0)
	s_barrier
	s_setprio 2

; #define SBAR() __builtin_amdgcn_sched_barrier(0)
; DI void expsum(f32x16& p, float& l_reg, bf16x8& pa0, bf16x8& pa1) {
; #pragma unroll
;     for (int r = 0; r < 16; ++r) p[r] = __builtin_amdgcn_exp2f(p[r]);
;     float ps = 0.f;
; #pragma unroll
;     for (int r = 0; r < 16; ++r) ps += p[r];
;     l_reg += ps; asm volatile("" : "+v"(l_reg));
;     ...
;     ATT_PK4(p, 0, pa0); ATT_PK4(p, 8, pa1);
;     ...
; }
; DI int v_rd_base(int lane) { return ((lane & 3) << 3) | (((lane >> 2) & 3) << 6) | (((lane >> 4) & 1) << 5) | (((lane >> 5) & 1) << 8); }
; template <int OFF> DI s16x4 tr_read(int vb) { s16x4 r; asm volatile("ds_read_b64_tr_b16 %0, %1 offset:%2" : "=&v"(r) : "v"(vb), "i"(OFF) : "memory"); return r; }
; template <int H> DI void v_reads(s16x4* vf, int vb) {
;     vf[0] = tr_read<v_rd_off(0, 2 * H, 0)>(vb); vf[1] = tr_read<v_rd_off(0, 2 * H, 1)>(vb); vf[2] = tr_read<v_rd_off(0, 2 * H + 1, 0)>(vb); vf[3] = tr_read<v_rd_off(0, 2 * H + 1, 1)>(vb);
;     vf[4] = tr_read<v_rd_off(1, 2 * H, 0)>(vb); vf[5] = tr_read<v_rd_off(1, 2 * H, 1)>(vb); vf[6] = tr_read<v_rd_off(1, 2 * H + 1, 0)>(vb); vf[7] = tr_read<v_rd_off(1, 2 * H + 1, 1)>(vb);
;     vf[8] = tr_read<v_rd_off(2, 2 * H, 0)>(vb); vf[9] = tr_read<v_rd_off(2, 2 * H, 1)>(vb); vf[10] = tr_read<v_rd_off(2, 2 * H + 1, 0)>(vb); vf[11] = tr_read<v_rd_off(2, 2 * H + 1, 1)>(vb);
;     vf[12] = tr_read<v_rd_off(3, 2 * H, 0)>(vb); vf[13] = tr_read<v_rd_off(3, 2 * H, 1)>(vb); vf[14] = tr_read<v_rd_off(3, 2 * H + 1, 0)>(vb); vf[15] = tr_read<v_rd_off(3, 2 * H + 1, 1)>(vb);
; }
; template <int DQK, int MODE, int LDQ, int LDK, int LDV> ...
;     ...
;     constexpr int NDA = ND0 > 6 ? 6 : ND0;
;     ...
;     f32x16 pA, pB; bf16x8 pa0, pa1;
;     int v0 = 0, v1 = 1, v2 = 2;
;     ATT_TOP(NKP + 2);
;     { bf16x8 kf[NDA]; k_reads<DQK, 0, NDA>(kf, lds, 0, r32, hi); ATT_LGKM0(); qk_mma<0, NDA>(pA, kf, qr);
;       if constexpr (ND0 > NDA) { bf16x8 kg[ND0 - NDA]; k_reads<DQK, NDA, ND0>(kg, lds, 0, r32, hi); ATT_LGKM0(); qk_mma<NDA, ND0>(pA, kg, qr); }
;       ATT_BIAS(pA, 0, 0); }
;     if (wid >= 4) __builtin_amdgcn_s_setprio(1);
;     for (int j = 0; j < NT; ++j) {
;         if (j + 2 < NT) ATT_TOP(NKP + 2); else ATT_TOP(0);
;         if (j + 3 < NT) ATT_DMA_K(j + 3);
;         if (j + 2 < NT) ATT_DMA_V(j + 2, v2);
;         ATT_SEG(j); SBAR();
;         ATT_STEP(pA, pB, 0, v0, true, 1, j);
;         ATT_STEP(pB, pA, 1, v0, (j + 1 < NT), 0, j + 1);
.LBB0_1938:
	ds_read_b128 v[100:103], v107 offset:24576
	ds_read_b128 v[114:117], v108 offset:24576
	ds_read_b128 v[118:121], v109 offset:24576
	ds_read_b128 v[122:125], v110 offset:24576
	ds_read_b64_tr_b16 v[132:133], v98 offset:0x2000
	ds_read_b64_tr_b16 v[134:135], v98 offset:0x2800
	ds_read_b64_tr_b16 v[136:137], v98 offset:0x3000
	ds_read_b64_tr_b16 v[138:139], v98 offset:0x3800
	ds_read_b64_tr_b16 v[140:141], v98 offset:0x2200
	ds_read_b64_tr_b16 v[142:143], v98 offset:0x2a00
	ds_read_b64_tr_b16 v[144:145], v98 offset:0x3200
	ds_read_b64_tr_b16 v[146:147], v98 offset:0x3a00
	ds_read_b64_tr_b16 v[148:149], v98 offset:0x2400
	ds_read_b64_tr_b16 v[150:151], v98 offset:0x2c00
	ds_read_b64_tr_b16 v[152:153], v98 offset:0x3400
	ds_read_b64_tr_b16 v[154:155], v98 offset:0x3c00
	ds_read_b64_tr_b16 v[156:157], v98 offset:0x2600
	ds_read_b64_tr_b16 v[158:159], v98 offset:0x2e00
	ds_read_b64_tr_b16 v[162:163], v98 offset:0x3600
	ds_read_b64_tr_b16 v[164:165], v98 offset:0x3e00
	s_nop 6
	s_setprio 2
	v_exp_f32_e32 v64, v64
	v_exp_f32_e32 v65, v65
	v_exp_f32_e32 v66, v66
	v_exp_f32_e32 v67, v67
	v_exp_f32_e32 v68, v68
	v_add_f32_e32 v97, 0, v64
	v_exp_f32_e32 v69, v69
	v_add_f32_e32 v97, v65, v97
	v_exp_f32_e32 v70, v70
	v_add_f32_e32 v97, v66, v97
	v_exp_f32_e32 v71, v71
	v_add_f32_e32 v97, v67, v97
	v_exp_f32_e32 v72, v72
	v_add_f32_e32 v97, v68, v97
	v_exp_f32_e32 v73, v73
	v_add_f32_e32 v97, v69, v97
	v_exp_f32_e32 v74, v74
	v_add_f32_e32 v97, v70, v97
	v_exp_f32_e32 v75, v75
	v_add_f32_e32 v97, v71, v97
	v_exp_f32_e32 v76, v76
	v_add_f32_e32 v97, v72, v97
	v_exp_f32_e32 v77, v77
	v_add_f32_e32 v97, v73, v97
	v_exp_f32_e32 v78, v78
	v_add_f32_e32 v97, v74, v97
	v_exp_f32_e32 v79, v79
	v_add_f32_e32 v97, v75, v97
	v_add_f32_e32 v97, v76, v97
	v_add_f32_e32 v97, v77, v97
	v_add_f32_e32 v97, v78, v97
	v_add_f32_e32 v97, v79, v97
	v_add_f32_e32 v96, v96, v97
	v_cvt_pk_bf16_f32 v64, v64, v65
	v_cvt_pk_bf16_f32 v65, v66, v67
	v_cvt_pk_bf16_f32 v66, v68, v69
	v_cvt_pk_bf16_f32 v67, v70, v71
	v_cvt_pk_bf16_f32 v68, v72, v73
	v_cvt_pk_bf16_f32 v69, v74, v75
	v_cvt_pk_bf16_f32 v70, v76, v77
	v_cvt_pk_bf16_f32 v71, v78, v79
	s_nop 0
	v_permlane32_swap_b32_e32 v64, v66
	v_permlane32_swap_b32_e32 v65, v67
	v_permlane32_swap_b32_e32 v68, v70
	v_permlane32_swap_b32_e32 v69, v71
	s_waitcnt lgkmcnt(0)
	s_setprio 1
	s_cmp_lt_u32 s33, 0x100
	s_cbranch_scc1 .Lstg_d0_m62_15
	s_waitcnt vmcnt(0)
	s_barrier
	s_setprio 2

; #define SBAR() __builtin_amdgcn_sched_barrier(0)
; DI void expsum(f32x16& p, float& l_reg, bf16x8& pa0, bf16x8& pa1) {
; #pragma unroll
;     for (int r = 0; r < 16; ++r) p[r] = __builtin_amdgcn_exp2f(p[r]);
;     float ps = 0.f;
; #pragma unroll
;     for (int r = 0; r < 16; ++r) ps += p[r];
;     l_reg += ps; asm volatile("" : "+v"(l_reg));
;     ...
;     ATT_PK4(p, 0, pa0); ATT_PK4(p, 8, pa1);
;     ...
; }
; DI int v_rd_base(int lane) { return ((lane & 3) << 3) | (((lane >> 2) & 3) << 6) | (((lane >> 4) & 1) << 5) | (((lane >> 5) & 1) << 8); }
; template <int OFF> DI s16x4 tr_read(int vb) { s16x4 r; asm volatile("ds_read_b64_tr_b16 %0, %1 offset:%2" : "=&v"(r) : "v"(vb), "i"(OFF) : "memory"); return r; }
; template <int H> DI void v_reads(s16x4* vf, int vb) {
;     vf[0] = tr_read<v_rd_off(0, 2 * H, 0)>(vb); vf[1] = tr_read<v_rd_off(0, 2 * H, 1)>(vb); vf[2] = tr_read<v_rd_off(0, 2 * H + 1, 0)>(vb); vf[3] = tr_read<v_rd_off(0, 2 * H + 1, 1)>(vb);
;     vf[4] = tr_read<v_rd_off(1, 2 * H, 0)>(vb); vf[5] = tr_read<v_rd_off(1, 2 * H, 1)>(vb); vf[6] = tr_read<v_rd_off(1, 2 * H + 1, 0)>(vb); vf[7] = tr_read<v_rd_off(1, 2 * H + 1, 1)>(vb);
;     vf[8] = tr_read<v_rd_off(2, 2 * H, 0)>(vb); vf[9] = tr_read<v_rd_off(2, 2 * H, 1)>(vb); vf[10] = tr_read<v_rd_off(2, 2 * H + 1, 0)>(vb); vf[11] = tr_read<v_rd_off(2, 2 * H + 1, 1)>(vb);
;     vf[12] = tr_read<v_rd_off(3, 2 * H, 0)>(vb); vf[13] = tr_read<v_rd_off(3, 2 * H, 1)>(vb); vf[14] = tr_read<v_rd_off(3, 2 * H + 1, 0)>(vb); vf[15] = tr_read<v_rd_off(3, 2 * H + 1, 1)>(vb);
; }
; template <int DQK, int MODE, int LDQ, int LDK, int LDV> ...
;     ...
;     constexpr int NDA = ND0 > 6 ? 6 : ND0;
;     ...
;     f32x16 pA, pB; bf16x8 pa0, pa1;
;     int v0 = 0, v1 = 1, v2 = 2;
;     ATT_TOP(NKP + 2);
;     { bf16x8 kf[NDA]; k_reads<DQK, 0, NDA>(kf, lds, 0, r32, hi); ATT_LGKM0(); qk_mma<0, NDA>(pA, kf, qr);
;       if constexpr (ND0 > NDA) { bf16x8 kg[ND0 - NDA]; k_reads<DQK, NDA, ND0>(kg, lds, 0, r32, hi); ATT_LGKM0(); qk_mma<NDA, ND0>(pA, kg, qr); }
;       ATT_BIAS(pA, 0, 0); }
;     if (wid >= 4) __builtin_amdgcn_s_setprio(1);
;     for (int j = 0; j < NT; ++j) {
;         if (j + 2 < NT) ATT_TOP(NKP + 2); else ATT_TOP(0);
;         if (j + 3 < NT) ATT_DMA_K(j + 3);
;         if (j + 2 < NT) ATT_DMA_V(j + 2, v2);
;         ATT_SEG(j); SBAR();
;         ATT_STEP(pA, pB, 0, v0, true, 1, j);
;         ATT_STEP(pB, pA, 1, v0, (j + 1 < NT), 0, j + 1);
.LBB0_1963:
	ds_read_b128 v[98:101], v107 offset:16384
	ds_read_b128 v[102:105], v108 offset:16384
	ds_read_b128 v[114:117], v109 offset:16384
	ds_read_b128 v[118:121], v110 offset:16384
	ds_read_b64_tr_b16 v[122:123], v96 offset:0x2000
	ds_read_b64_tr_b16 v[124:125], v96 offset:0x2800
	ds_read_b64_tr_b16 v[132:133], v96 offset:0x3000
	ds_read_b64_tr_b16 v[134:135], v96 offset:0x3800
	ds_read_b64_tr_b16 v[136:137], v96 offset:0x2200
	ds_read_b64_tr_b16 v[138:139], v96 offset:0x2a00
	ds_read_b64_tr_b16 v[140:141], v96 offset:0x3200
	ds_read_b64_tr_b16 v[142:143], v96 offset:0x3a00
	ds_read_b64_tr_b16 v[144:145], v96 offset:0x2400
	ds_read_b64_tr_b16 v[146:147], v96 offset:0x2c00
	ds_read_b64_tr_b16 v[148:149], v96 offset:0x3400
	ds_read_b64_tr_b16 v[150:151], v96 offset:0x3c00
	ds_read_b64_tr_b16 v[152:153], v96 offset:0x2600
	ds_read_b64_tr_b16 v[154:155], v96 offset:0x2e00
	ds_read_b64_tr_b16 v[156:157], v96 offset:0x3600
	ds_read_b64_tr_b16 v[158:159], v96 offset:0x3e00
	s_nop 6
	s_setprio 2
	v_exp_f32_e32 v64, v64
	v_exp_f32_e32 v65, v65
	v_exp_f32_e32 v66, v66
	v_exp_f32_e32 v67, v67
	v_exp_f32_e32 v68, v68
	v_add_f32_e32 v96, 0, v64
	v_exp_f32_e32 v69, v69
	v_add_f32_e32 v96, v65, v96
	v_exp_f32_e32 v70, v70
	v_add_f32_e32 v96, v66, v96
	v_exp_f32_e32 v71, v71
	v_add_f32_e32 v96, v67, v96
	v_exp_f32_e32 v72, v72
	v_add_f32_e32 v96, v68, v96
	v_exp_f32_e32 v73, v73
	v_add_f32_e32 v96, v69, v96
	v_exp_f32_e32 v74, v74
	v_add_f32_e32 v96, v70, v96
	v_exp_f32_e32 v75, v75
	v_add_f32_e32 v96, v71, v96
	v_exp_f32_e32 v76, v76
	v_add_f32_e32 v96, v72, v96
	v_exp_f32_e32 v77, v77
	v_add_f32_e32 v96, v73, v96
	v_exp_f32_e32 v78, v78
	v_add_f32_e32 v96, v74, v96
	v_exp_f32_e32 v79, v79
	v_add_f32_e32 v96, v75, v96
	v_add_f32_e32 v96, v76, v96
	v_add_f32_e32 v96, v77, v96
	v_add_f32_e32 v96, v78, v96
	v_add_f32_e32 v96, v79, v96
	v_add_f32_e32 v96, v97, v96
	v_cvt_pk_bf16_f32 v64, v64, v65
	v_cvt_pk_bf16_f32 v65, v66, v67
	v_cvt_pk_bf16_f32 v66, v68, v69
	v_cvt_pk_bf16_f32 v67, v70, v71
	v_cvt_pk_bf16_f32 v68, v72, v73
	v_cvt_pk_bf16_f32 v69, v74, v75
	v_cvt_pk_bf16_f32 v70, v76, v77
	v_cvt_pk_bf16_f32 v71, v78, v79
	s_nop 0
	v_permlane32_swap_b32_e32 v64, v66
	v_permlane32_swap_b32_e32 v65, v67
	v_permlane32_swap_b32_e32 v68, v70
	v_permlane32_swap_b32_e32 v69, v71
	s_waitcnt lgkmcnt(0)
	s_setprio 1
	s_cmp_lt_u32 s33, 0x100
	s_cbranch_scc1 .Lstg_d1_m61_21
	s_waitcnt vmcnt(0)
	s_barrier
	s_setprio 2

; #define LAS __attribute__((address_space(3)))
; DI void expsum(f32x16& p, float& l_reg, bf16x8& pa0, bf16x8& pa1) {
; #pragma unroll
;     for (int r = 0; r < 16; ++r) p[r] = __builtin_amdgcn_exp2f(p[r]);
;     float ps = 0.f;
; #pragma unroll
;     for (int r = 0; r < 16; ++r) ps += p[r];
;     l_reg += ps; asm volatile("" : "+v"(l_reg));
;     ...
;     ATT_PK4(p, 0, pa0); ATT_PK4(p, 8, pa1);
;     ...
; }
; DI int v_rd_base(int lane) { return ((lane & 3) << 3) | (((lane >> 2) & 3) << 6) | (((lane >> 4) & 1) << 5) | (((lane >> 5) & 1) << 8); }
; template <int OFF> DI s16x4 tr_read(int vb) { s16x4 r; asm volatile("ds_read_b64_tr_b16 %0, %1 offset:%2" : "=&v"(r) : "v"(vb), "i"(OFF) : "memory"); return r; }
; template <int H> DI void v_reads(s16x4* vf, int vb) {
;     vf[0] = tr_read<v_rd_off(0, 2 * H, 0)>(vb); vf[1] = tr_read<v_rd_off(0, 2 * H, 1)>(vb); vf[2] = tr_read<v_rd_off(0, 2 * H + 1, 0)>(vb); vf[3] = tr_read<v_rd_off(0, 2 * H + 1, 1)>(vb);
;     vf[4] = tr_read<v_rd_off(1, 2 * H, 0)>(vb); vf[5] = tr_read<v_rd_off(1, 2 * H, 1)>(vb); vf[6] = tr_read<v_rd_off(1, 2 * H + 1, 0)>(vb); vf[7] = tr_read<v_rd_off(1, 2 * H + 1, 1)>(vb);
;     vf[8] = tr_read<v_rd_off(2, 2 * H, 0)>(vb); vf[9] = tr_read<v_rd_off(2, 2 * H, 1)>(vb); vf[10] = tr_read<v_rd_off(2, 2 * H + 1, 0)>(vb); vf[11] = tr_read<v_rd_off(2, 2 * H + 1, 1)>(vb);
;     vf[12] = tr_read<v_rd_off(3, 2 * H, 0)>(vb); vf[13] = tr_read<v_rd_off(3, 2 * H, 1)>(vb); vf[14] = tr_read<v_rd_off(3, 2 * H + 1, 0)>(vb); vf[15] = tr_read<v_rd_off(3, 2 * H + 1, 1)>(vb);
; }
; DI void pv_mma(f32x16* o, const s16x4* vf, bf16x8 pa0, bf16x8 pa1) {
;     ...
; #pragma unroll
;     for (int d0 = 0; d0 < 4; ++d0) {
;         o[d0] = __builtin_amdgcn_mfma_f32_32x32x16_bf16(pa0, ATT_PK(vf[4 * d0], vf[4 * d0 + 1]), o[d0], 0, 0, 0);
;         o[d0] = __builtin_amdgcn_mfma_f32_32x32x16_bf16(pa1, ATT_PK(vf[4 * d0 + 2], vf[4 * d0 + 3]), o[d0], 0, 0, 0); }
;     ...
; }
; template <int DQK, int D0A, int D0B> DI void k_reads(bf16x8* kf, const LAS unsigned char* Ks, int half, int r32, int hi) {
; #pragma unroll
;     for (int d0 = D0A; d0 < D0B; ++d0) kf[d0 - D0A] = *(const LAS bf16x8*)(Ks + half * (32 * DQK * 2) + kswz<DQK>(r32, (d0 * 16 + hi * 8) * 2));
; }
.Lstg_mla_top_2:
	s_setprio 0
	s_mov_b32 m0, s1
	s_mov_b32 s0, s5
	s_mov_b32 s5, s44
	s_mov_b32 s44, s4
	s_lshl_b32 s4, s4, 14
	global_load_lds_dwordx4 v136, s[34:35]
	s_add_i32 m0, s1, 0x2000
	s_add_i32 s4, s52, s4
	global_load_lds_dwordx4 v138, s[34:35]
	s_add_i32 m0, s1, 0x4000
	s_add_i32 s6, s4, 0x400
	global_load_lds_dwordx4 v140, s[34:35]
	s_mov_b32 m0, s4
	s_add_i32 s1, s43, -3
	global_load_lds_dwordx4 v144, s[34:35]
	s_mov_b32 m0, s6
	s_nop 0
	global_load_lds_dwordx4 v142, s[34:35]
	s_and_b32 s1, s1, 3
	s_mulk_i32 s1, 0x6000
	v_add_u32_e32 v246, s1, v158
	v_add_u32_e32 v174, v246, v151
	v_add_u32_e32 v178, v246, v149
	v_add_u32_e32 v182, v246, v148
	v_add_u32_e32 v186, v246, v147
	v_add_u32_e32 v190, v246, v146
	v_add_u32_e32 v194, v246, v150
	s_lshl_b32 s1, s0, 14
	ds_read_b128 v[174:177], v174 offset:12288
	ds_read_b128 v[178:181], v178 offset:12288
	ds_read_b128 v[182:185], v182 offset:12288
	ds_read_b128 v[186:189], v186 offset:12288
	ds_read_b128 v[190:193], v190 offset:12288
	ds_read_b128 v[194:197], v194 offset:12288
	v_add_u32_e32 v254, s1, v130
	ds_read_b64_tr_b16 v[198:199], v254 offset:0
	ds_read_b64_tr_b16 v[200:201], v254 offset:0x800
	ds_read_b64_tr_b16 v[202:203], v254 offset:0x1000
	ds_read_b64_tr_b16 v[204:205], v254 offset:0x1800
	ds_read_b64_tr_b16 v[206:207], v254 offset:0x200
	ds_read_b64_tr_b16 v[208:209], v254 offset:0xa00
	ds_read_b64_tr_b16 v[210:211], v254 offset:0x1200
	ds_read_b64_tr_b16 v[212:213], v254 offset:0x1a00
	ds_read_b64_tr_b16 v[214:215], v254 offset:0x400
	ds_read_b64_tr_b16 v[216:217], v254 offset:0xc00
	ds_read_b64_tr_b16 v[218:219], v254 offset:0x1400
	ds_read_b64_tr_b16 v[220:221], v254 offset:0x1c00
	ds_read_b64_tr_b16 v[222:223], v254 offset:0x600
	ds_read_b64_tr_b16 v[224:225], v254 offset:0xe00
	ds_read_b64_tr_b16 v[226:227], v254 offset:0x1600
	ds_read_b64_tr_b16 v[228:229], v254 offset:0x1e00
	s_setprio 2
	v_exp_f32_e32 v64, v64
	v_exp_f32_e32 v65, v65
	v_exp_f32_e32 v66, v66
	v_exp_f32_e32 v67, v67
	v_exp_f32_e32 v68, v68
	v_add_f32_e32 v230, 0, v64
	v_exp_f32_e32 v69, v69
	v_add_f32_e32 v230, v65, v230
	v_exp_f32_e32 v70, v70
	v_add_f32_e32 v230, v66, v230
	v_exp_f32_e32 v71, v71
	v_add_f32_e32 v230, v67, v230
	v_exp_f32_e32 v72, v72
	v_add_f32_e32 v230, v68, v230
	v_exp_f32_e32 v73, v73
	v_add_f32_e32 v230, v69, v230
	v_exp_f32_e32 v74, v74
	v_add_f32_e32 v230, v70, v230
	v_exp_f32_e32 v75, v75
	v_add_f32_e32 v230, v71, v230
	v_exp_f32_e32 v76, v76
	v_add_f32_e32 v230, v72, v230
	v_exp_f32_e32 v77, v77
	v_add_f32_e32 v230, v73, v230
	v_exp_f32_e32 v78, v78
	v_add_f32_e32 v230, v74, v230
	v_exp_f32_e32 v79, v79
	v_add_f32_e32 v230, v75, v230
	v_add_f32_e32 v230, v76, v230
	v_add_f32_e32 v230, v77, v230
	v_add_f32_e32 v230, v78, v230
	v_add_f32_e32 v230, v79, v230
	v_add_f32_e32 v173, v173, v230
	v_cvt_pk_bf16_f32 v64, v64, v65
	v_cvt_pk_bf16_f32 v65, v66, v67
	v_cvt_pk_bf16_f32 v66, v68, v69
	v_cvt_pk_bf16_f32 v67, v70, v71
	v_cvt_pk_bf16_f32 v68, v72, v73
	v_cvt_pk_bf16_f32 v69, v74, v75
	v_cvt_pk_bf16_f32 v70, v76, v77
	v_cvt_pk_bf16_f32 v71, v78, v79
	s_nop 0
	v_permlane32_swap_b32_e32 v64, v66
	v_permlane32_swap_b32_e32 v65, v67
	v_permlane32_swap_b32_e32 v68, v70
	v_permlane32_swap_b32_e32 v69, v71
	s_waitcnt lgkmcnt(0)
	v_add_u32_e32 v72, v246, v152
	v_add_u32_e32 v73, v246, v153
	ds_read_b128 v[230:233], v72 offset:12288
	ds_read_b128 v[234:237], v73 offset:12288
	v_add_u32_e32 v72, v246, v154
	v_add_u32_e32 v73, v246, v155
	ds_read_b128 v[238:241], v72 offset:12288
	ds_read_b128 v[242:245], v73 offset:12288
	v_add_u32_e32 v72, v246, v156
	v_add_u32_e32 v73, v246, v157
	ds_read_b128 v[246:249], v72 offset:12288
	ds_read_b128 v[250:253], v73 offset:12288
	s_setprio 1
	v_mfma_f32_32x32x16_bf16 v[48:63], v[64:67], v[198:201], v[48:63]
	v_mfma_f32_32x32x16_bf16 v[32:47], v[64:67], v[206:209], v[32:47]
	v_mfma_f32_32x32x16_bf16 v[16:31], v[64:67], v[214:217], v[16:31]
	v_mfma_f32_32x32x16_bf16 v[0:15], v[64:67], v[222:225], v[0:15]
	v_mfma_f32_32x32x16_bf16 v[48:63], v[68:71], v[202:205], v[48:63]
	v_mfma_f32_32x32x16_bf16 v[32:47], v[68:71], v[210:213], v[32:47]
	v_mfma_f32_32x32x16_bf16 v[16:31], v[68:71], v[218:221], v[16:31]
	v_mfma_f32_32x32x16_bf16 v[0:15], v[68:71], v[226:229], v[0:15]
	s_waitcnt lgkmcnt(0)
; #define LAS __attribute__((address_space(3)))
; DI void expsum(f32x16& p, float& l_reg, bf16x8& pa0, bf16x8& pa1) {
; #pragma unroll
;     for (int r = 0; r < 16; ++r) p[r] = __builtin_amdgcn_exp2f(p[r]);
;     float ps = 0.f;
; #pragma unroll
;     for (int r = 0; r < 16; ++r) ps += p[r];
;     l_reg += ps; asm volatile("" : "+v"(l_reg));
;     ...
;     ATT_PK4(p, 0, pa0); ATT_PK4(p, 8, pa1);
;     ...
; }
; DI int v_rd_base(int lane) { return ((lane & 3) << 3) | (((lane >> 2) & 3) << 6) | (((lane >> 4) & 1) << 5) | (((lane >> 5) & 1) << 8); }
; template <int OFF> DI s16x4 tr_read(int vb) { s16x4 r; asm volatile("ds_read_b64_tr_b16 %0, %1 offset:%2" : "=&v"(r) : "v"(vb), "i"(OFF) : "memory"); return r; }
; template <int H> DI void v_reads(s16x4* vf, int vb) {
;     vf[0] = tr_read<v_rd_off(0, 2 * H, 0)>(vb); vf[1] = tr_read<v_rd_off(0, 2 * H, 1)>(vb); vf[2] = tr_read<v_rd_off(0, 2 * H + 1, 0)>(vb); vf[3] = tr_read<v_rd_off(0, 2 * H + 1, 1)>(vb);
;     vf[4] = tr_read<v_rd_off(1, 2 * H, 0)>(vb); vf[5] = tr_read<v_rd_off(1, 2 * H, 1)>(vb); vf[6] = tr_read<v_rd_off(1, 2 * H + 1, 0)>(vb); vf[7] = tr_read<v_rd_off(1, 2 * H + 1, 1)>(vb);
;     vf[8] = tr_read<v_rd_off(2, 2 * H, 0)>(vb); vf[9] = tr_read<v_rd_off(2, 2 * H, 1)>(vb); vf[10] = tr_read<v_rd_off(2, 2 * H + 1, 0)>(vb); vf[11] = tr_read<v_rd_off(2, 2 * H + 1, 1)>(vb);
;     vf[12] = tr_read<v_rd_off(3, 2 * H, 0)>(vb); vf[13] = tr_read<v_rd_off(3, 2 * H, 1)>(vb); vf[14] = tr_read<v_rd_off(3, 2 * H + 1, 0)>(vb); vf[15] = tr_read<v_rd_off(3, 2 * H + 1, 1)>(vb);
; }
; DI void pv_mma(f32x16* o, const s16x4* vf, bf16x8 pa0, bf16x8 pa1) {
;     ...
; #pragma unroll
;     for (int d0 = 0; d0 < 4; ++d0) {
;         o[d0] = __builtin_amdgcn_mfma_f32_32x32x16_bf16(pa0, ATT_PK(vf[4 * d0], vf[4 * d0 + 1]), o[d0], 0, 0, 0);
;         o[d0] = __builtin_amdgcn_mfma_f32_32x32x16_bf16(pa1, ATT_PK(vf[4 * d0 + 2], vf[4 * d0 + 3]), o[d0], 0, 0, 0); }
;     ...
; }
; template <int DQK, int D0A, int D0B> DI void k_reads(bf16x8* kf, const LAS unsigned char* Ks, int half, int r32, int hi) {
; #pragma unroll
;     for (int d0 = D0A; d0 < D0B; ++d0) kf[d0 - D0A] = *(const LAS bf16x8*)(Ks + half * (32 * DQK * 2) + kswz<DQK>(r32, (d0 * 16 + hi * 8) * 2));
; }
; template <int D0A, int D0B> DI void qk_mma(f32x16& p, const bf16x8* kf, const bf16x8* qr) {
; #pragma unroll
;     for (int d0 = D0A; d0 < D0B; ++d0) {
	v_mfma_f32_32x32x16_bf16 v[64:79], v[174:177], v[80:83], 0
	v_mfma_f32_32x32x16_bf16 v[64:79], v[178:181], v[84:87], v[64:79]
	v_mfma_f32_32x32x16_bf16 v[64:79], v[182:185], v[88:91], v[64:79]
	v_mfma_f32_32x32x16_bf16 v[64:79], v[186:189], v[92:95], v[64:79]
	v_mfma_f32_32x32x16_bf16 v[64:79], v[190:193], v[96:99], v[64:79]
	v_mfma_f32_32x32x16_bf16 v[64:79], v[194:197], v[100:103], v[64:79]
	v_mfma_f32_32x32x16_bf16 v[64:79], v[230:233], v[104:107], v[64:79]
	v_mfma_f32_32x32x16_bf16 v[64:79], v[234:237], v[108:111], v[64:79]
	v_mfma_f32_32x32x16_bf16 v[64:79], v[238:241], v[112:115], v[64:79]
	v_mfma_f32_32x32x16_bf16 v[64:79], v[242:245], v[116:119], v[64:79]
	v_mfma_f32_32x32x16_bf16 v[64:79], v[246:249], v[120:123], v[64:79]
	v_mfma_f32_32x32x16_bf16 v[64:79], v[250:253], v[124:127], v[64:79]
	s_setprio 0
	s_add_i32 s4, s43, -2
	s_and_b32 s4, s4, 3
	s_mulk_i32 s4, 0x6000
	v_add_u32_e32 v246, s4, v158
	v_add_u32_e32 v174, v246, v151
	v_add_u32_e32 v178, v246, v149
	v_add_u32_e32 v182, v246, v148
	v_add_u32_e32 v186, v246, v147
	v_add_u32_e32 v190, v246, v146
	v_add_u32_e32 v194, v246, v150
	ds_read_b128 v[174:177], v174
	ds_read_b128 v[178:181], v178
	ds_read_b128 v[182:185], v182
	ds_read_b128 v[186:189], v186
	ds_read_b128 v[190:193], v190
	ds_read_b128 v[194:197], v194
	ds_read_b64_tr_b16 v[198:199], v254 offset:0x2000
	ds_read_b64_tr_b16 v[200:201], v254 offset:0x2800
	ds_read_b64_tr_b16 v[202:203], v254 offset:0x3000
	ds_read_b64_tr_b16 v[204:205], v254 offset:0x3800
	ds_read_b64_tr_b16 v[206:207], v254 offset:0x2200
	ds_read_b64_tr_b16 v[208:209], v254 offset:0x2a00
	ds_read_b64_tr_b16 v[210:211], v254 offset:0x3200
	ds_read_b64_tr_b16 v[212:213], v254 offset:0x3a00
	ds_read_b64_tr_b16 v[214:215], v254 offset:0x2400
	ds_read_b64_tr_b16 v[216:217], v254 offset:0x2c00
	ds_read_b64_tr_b16 v[218:219], v254 offset:0x3400
	ds_read_b64_tr_b16 v[220:221], v254 offset:0x3c00
	ds_read_b64_tr_b16 v[222:223], v254 offset:0x2600
	ds_read_b64_tr_b16 v[224:225], v254 offset:0x2e00
	ds_read_b64_tr_b16 v[226:227], v254 offset:0x3600
	ds_read_b64_tr_b16 v[228:229], v254 offset:0x3e00
	s_setprio 2
	v_exp_f32_e32 v64, v64
	v_exp_f32_e32 v65, v65
	v_exp_f32_e32 v66, v66
	v_exp_f32_e32 v67, v67
	v_exp_f32_e32 v68, v68
	v_add_f32_e32 v230, 0, v64
	v_exp_f32_e32 v69, v69
	v_add_f32_e32 v230, v65, v230
	v_exp_f32_e32 v70, v70
	v_add_f32_e32 v230, v66, v230
	v_exp_f32_e32 v71, v71
	v_add_f32_e32 v230, v67, v230
	v_exp_f32_e32 v72, v72
	v_add_f32_e32 v230, v68, v230
	v_exp_f32_e32 v73, v73
	v_add_f32_e32 v230, v69, v230
	v_exp_f32_e32 v74, v74
	v_add_f32_e32 v230, v70, v230
	v_exp_f32_e32 v75, v75
	v_add_f32_e32 v230, v71, v230
	v_exp_f32_e32 v76, v76
	v_add_f32_e32 v230, v72, v230
	v_exp_f32_e32 v77, v77
	v_add_f32_e32 v230, v73, v230
	v_exp_f32_e32 v78, v78
	v_add_f32_e32 v230, v74, v230
	v_exp_f32_e32 v79, v79
	v_add_f32_e32 v230, v75, v230
	v_add_f32_e32 v230, v76, v230
	v_add_f32_e32 v230, v77, v230
	v_add_f32_e32 v230, v78, v230
	v_add_f32_e32 v230, v79, v230
	v_add_f32_e32 v173, v173, v230
	v_cvt_pk_bf16_f32 v64, v64, v65
	v_cvt_pk_bf16_f32 v65, v66, v67
	v_cvt_pk_bf16_f32 v66, v68, v69
	v_cvt_pk_bf16_f32 v67, v70, v71
	v_cvt_pk_bf16_f32 v68, v72, v73
	v_cvt_pk_bf16_f32 v69, v74, v75
	v_cvt_pk_bf16_f32 v70, v76, v77
	v_cvt_pk_bf16_f32 v71, v78, v79
	s_nop 0
	v_permlane32_swap_b32_e32 v64, v66
	v_permlane32_swap_b32_e32 v65, v67
	v_permlane32_swap_b32_e32 v68, v70
	v_permlane32_swap_b32_e32 v69, v71
	s_waitcnt lgkmcnt(0)
	v_add_u32_e32 v72, v246, v152
	v_add_u32_e32 v73, v246, v153
	ds_read_b128 v[230:233], v72
	ds_read_b128 v[234:237], v73
	v_add_u32_e32 v72, v246, v154
	v_add_u32_e32 v73, v246, v155
	ds_read_b128 v[238:241], v72
	ds_read_b128 v[242:245], v73
	v_add_u32_e32 v72, v246, v156
	v_add_u32_e32 v73, v246, v157
	ds_read_b128 v[246:249], v72
	ds_read_b128 v[250:253], v73
	s_setprio 1
	s_cmp_lt_u32 s33, 0x100
	s_cbranch_scc1 .Lstg_mla_mid_3
	s_waitcnt vmcnt(5)
	s_barrier
	s_setprio 2

; #define LAS __attribute__((address_space(3)))
; DI void expsum(f32x16& p, float& l_reg, bf16x8& pa0, bf16x8& pa1) {
; #pragma unroll
;     for (int r = 0; r < 16; ++r) p[r] = __builtin_amdgcn_exp2f(p[r]);
;     float ps = 0.f;
; #pragma unroll
;     for (int r = 0; r < 16; ++r) ps += p[r];
;     l_reg += ps; asm volatile("" : "+v"(l_reg));
;     ...
;     ATT_PK4(p, 0, pa0); ATT_PK4(p, 8, pa1);
;     ...
; }
; DI int v_rd_base(int lane) { return ((lane & 3) << 3) | (((lane >> 2) & 3) << 6) | (((lane >> 4) & 1) << 5) | (((lane >> 5) & 1) << 8); }
; template <int OFF> DI s16x4 tr_read(int vb) { s16x4 r; asm volatile("ds_read_b64_tr_b16 %0, %1 offset:%2" : "=&v"(r) : "v"(vb), "i"(OFF) : "memory"); return r; }
; template <int H> DI void v_reads(s16x4* vf, int vb) {
;     vf[0] = tr_read<v_rd_off(0, 2 * H, 0)>(vb); vf[1] = tr_read<v_rd_off(0, 2 * H, 1)>(vb); vf[2] = tr_read<v_rd_off(0, 2 * H + 1, 0)>(vb); vf[3] = tr_read<v_rd_off(0, 2 * H + 1, 1)>(vb);
;     vf[4] = tr_read<v_rd_off(1, 2 * H, 0)>(vb); vf[5] = tr_read<v_rd_off(1, 2 * H, 1)>(vb); vf[6] = tr_read<v_rd_off(1, 2 * H + 1, 0)>(vb); vf[7] = tr_read<v_rd_off(1, 2 * H + 1, 1)>(vb);
;     vf[8] = tr_read<v_rd_off(2, 2 * H, 0)>(vb); vf[9] = tr_read<v_rd_off(2, 2 * H, 1)>(vb); vf[10] = tr_read<v_rd_off(2, 2 * H + 1, 0)>(vb); vf[11] = tr_read<v_rd_off(2, 2 * H + 1, 1)>(vb);
;     vf[12] = tr_read<v_rd_off(3, 2 * H, 0)>(vb); vf[13] = tr_read<v_rd_off(3, 2 * H, 1)>(vb); vf[14] = tr_read<v_rd_off(3, 2 * H + 1, 0)>(vb); vf[15] = tr_read<v_rd_off(3, 2 * H + 1, 1)>(vb);
; }
; DI void pv_mma(f32x16* o, const s16x4* vf, bf16x8 pa0, bf16x8 pa1) {
;     ...
; #pragma unroll
;     for (int d0 = 0; d0 < 4; ++d0) {
;         o[d0] = __builtin_amdgcn_mfma_f32_32x32x16_bf16(pa0, ATT_PK(vf[4 * d0], vf[4 * d0 + 1]), o[d0], 0, 0, 0);
;         o[d0] = __builtin_amdgcn_mfma_f32_32x32x16_bf16(pa1, ATT_PK(vf[4 * d0 + 2], vf[4 * d0 + 3]), o[d0], 0, 0, 0); }
;     ...
; }
; template <int DQK, int D0A, int D0B> DI void k_reads(bf16x8* kf, const LAS unsigned char* Ks, int half, int r32, int hi) {
; #pragma unroll
;     for (int d0 = D0A; d0 < D0B; ++d0) kf[d0 - D0A] = *(const LAS bf16x8*)(Ks + half * (32 * DQK * 2) + kswz<DQK>(r32, (d0 * 16 + hi * 8) * 2));
; }
.Lstg_mla_t61_4:
	s_setprio 0
	v_lshl_add_u64 v[132:133], v[132:133], 1, s[0:1]
	s_mov_b32 m0, s6
	v_lshl_add_u64 v[134:135], v[134:135], 1, s[0:1]
	global_load_lds_dwordx4 v[132:133], off
	s_mov_b32 m0, s7
	s_nop 0
	global_load_lds_dwordx4 v[134:135], off
	ds_read_b128 v[132:135], v161 offset:36864
	ds_read_b128 v[136:139], v162 offset:36864
	ds_read_b128 v[140:143], v163 offset:36864
	ds_read_b128 v[174:177], v164 offset:36864
	ds_read_b128 v[178:181], v165 offset:36864
	ds_read_b128 v[182:185], v166 offset:36864
	v_lshl_add_u32 v144, s5, 14, v130
	ds_read_b64_tr_b16 v[186:187], v144 offset:0
	ds_read_b64_tr_b16 v[188:189], v144 offset:0x800
	ds_read_b64_tr_b16 v[190:191], v144 offset:0x1000
	ds_read_b64_tr_b16 v[192:193], v144 offset:0x1800
	ds_read_b64_tr_b16 v[194:195], v144 offset:0x200
	ds_read_b64_tr_b16 v[196:197], v144 offset:0xa00
	ds_read_b64_tr_b16 v[198:199], v144 offset:0x1200
	ds_read_b64_tr_b16 v[200:201], v144 offset:0x1a00
	ds_read_b64_tr_b16 v[202:203], v144 offset:0x400
	ds_read_b64_tr_b16 v[204:205], v144 offset:0xc00
	ds_read_b64_tr_b16 v[206:207], v144 offset:0x1400
	ds_read_b64_tr_b16 v[208:209], v144 offset:0x1c00
	ds_read_b64_tr_b16 v[210:211], v144 offset:0x600
	ds_read_b64_tr_b16 v[212:213], v144 offset:0xe00
	ds_read_b64_tr_b16 v[214:215], v144 offset:0x1600
	ds_read_b64_tr_b16 v[216:217], v144 offset:0x1e00
	s_setprio 2
	v_exp_f32_e32 v64, v64
	v_exp_f32_e32 v65, v65
	v_exp_f32_e32 v66, v66
	v_exp_f32_e32 v67, v67
	v_exp_f32_e32 v68, v68
	v_add_f32_e32 v145, 0, v64
	v_exp_f32_e32 v69, v69
	v_add_f32_e32 v145, v65, v145
	v_exp_f32_e32 v70, v70
	v_add_f32_e32 v145, v66, v145
	v_exp_f32_e32 v71, v71
	v_add_f32_e32 v145, v67, v145
	v_exp_f32_e32 v72, v72
	v_add_f32_e32 v145, v68, v145
	v_exp_f32_e32 v73, v73
	v_add_f32_e32 v145, v69, v145
	v_exp_f32_e32 v74, v74
	v_add_f32_e32 v145, v70, v145
	v_exp_f32_e32 v75, v75
	v_add_f32_e32 v145, v71, v145
	v_exp_f32_e32 v76, v76
	v_add_f32_e32 v145, v72, v145
	v_exp_f32_e32 v77, v77
	v_add_f32_e32 v145, v73, v145
	v_exp_f32_e32 v78, v78
	v_add_f32_e32 v145, v74, v145
	v_exp_f32_e32 v79, v79
	v_add_f32_e32 v145, v75, v145
	v_add_f32_e32 v145, v76, v145
	v_add_f32_e32 v145, v77, v145
	v_add_f32_e32 v145, v78, v145
	v_add_f32_e32 v145, v79, v145
	v_add_f32_e32 v145, v173, v145
	v_cvt_pk_bf16_f32 v64, v64, v65
	v_cvt_pk_bf16_f32 v65, v66, v67
	v_cvt_pk_bf16_f32 v66, v68, v69
	v_cvt_pk_bf16_f32 v67, v70, v71
	v_cvt_pk_bf16_f32 v68, v72, v73
	v_cvt_pk_bf16_f32 v69, v74, v75
	v_cvt_pk_bf16_f32 v70, v76, v77
	v_cvt_pk_bf16_f32 v71, v78, v79
	s_nop 0
	v_permlane32_swap_b32_e32 v64, v66
	v_permlane32_swap_b32_e32 v65, v67
	v_permlane32_swap_b32_e32 v68, v70
	v_permlane32_swap_b32_e32 v69, v71
	s_waitcnt lgkmcnt(0)
	ds_read_b128 v[218:221], v167 offset:36864
	ds_read_b128 v[222:225], v168 offset:36864
	ds_read_b128 v[226:229], v169 offset:36864
	ds_read_b128 v[230:233], v170 offset:36864
	ds_read_b128 v[234:237], v171 offset:36864
	ds_read_b128 v[238:241], v172 offset:36864
	s_setprio 1
	v_mfma_f32_32x32x16_bf16 v[48:63], v[64:67], v[186:189], v[48:63]
	v_mfma_f32_32x32x16_bf16 v[32:47], v[64:67], v[194:197], v[32:47]
	v_mfma_f32_32x32x16_bf16 v[16:31], v[64:67], v[202:205], v[16:31]
	v_mfma_f32_32x32x16_bf16 v[0:15], v[64:67], v[210:213], v[0:15]
	v_mfma_f32_32x32x16_bf16 v[48:63], v[68:71], v[190:193], v[48:63]
	v_mfma_f32_32x32x16_bf16 v[32:47], v[68:71], v[198:201], v[32:47]
	v_mfma_f32_32x32x16_bf16 v[16:31], v[68:71], v[206:209], v[16:31]
	v_mfma_f32_32x32x16_bf16 v[0:15], v[68:71], v[214:217], v[0:15]
	s_waitcnt lgkmcnt(0)
; #define LAS __attribute__((address_space(3)))
; DI void expsum(f32x16& p, float& l_reg, bf16x8& pa0, bf16x8& pa1) {
; #pragma unroll
;     for (int r = 0; r < 16; ++r) p[r] = __builtin_amdgcn_exp2f(p[r]);
;     float ps = 0.f;
; #pragma unroll
;     for (int r = 0; r < 16; ++r) ps += p[r];
;     l_reg += ps; asm volatile("" : "+v"(l_reg));
;     ...
;     ATT_PK4(p, 0, pa0); ATT_PK4(p, 8, pa1);
;     ...
; }
; DI int v_rd_base(int lane) { return ((lane & 3) << 3) | (((lane >> 2) & 3) << 6) | (((lane >> 4) & 1) << 5) | (((lane >> 5) & 1) << 8); }
; template <int OFF> DI s16x4 tr_read(int vb) { s16x4 r; asm volatile("ds_read_b64_tr_b16 %0, %1 offset:%2" : "=&v"(r) : "v"(vb), "i"(OFF) : "memory"); return r; }
; template <int H> DI void v_reads(s16x4* vf, int vb) {
;     vf[0] = tr_read<v_rd_off(0, 2 * H, 0)>(vb); vf[1] = tr_read<v_rd_off(0, 2 * H, 1)>(vb); vf[2] = tr_read<v_rd_off(0, 2 * H + 1, 0)>(vb); vf[3] = tr_read<v_rd_off(0, 2 * H + 1, 1)>(vb);
;     vf[4] = tr_read<v_rd_off(1, 2 * H, 0)>(vb); vf[5] = tr_read<v_rd_off(1, 2 * H, 1)>(vb); vf[6] = tr_read<v_rd_off(1, 2 * H + 1, 0)>(vb); vf[7] = tr_read<v_rd_off(1, 2 * H + 1, 1)>(vb);
;     vf[8] = tr_read<v_rd_off(2, 2 * H, 0)>(vb); vf[9] = tr_read<v_rd_off(2, 2 * H, 1)>(vb); vf[10] = tr_read<v_rd_off(2, 2 * H + 1, 0)>(vb); vf[11] = tr_read<v_rd_off(2, 2 * H + 1, 1)>(vb);
;     vf[12] = tr_read<v_rd_off(3, 2 * H, 0)>(vb); vf[13] = tr_read<v_rd_off(3, 2 * H, 1)>(vb); vf[14] = tr_read<v_rd_off(3, 2 * H + 1, 0)>(vb); vf[15] = tr_read<v_rd_off(3, 2 * H + 1, 1)>(vb);
; }
; DI void pv_mma(f32x16* o, const s16x4* vf, bf16x8 pa0, bf16x8 pa1) {
;     ...
; #pragma unroll
;     for (int d0 = 0; d0 < 4; ++d0) {
;         o[d0] = __builtin_amdgcn_mfma_f32_32x32x16_bf16(pa0, ATT_PK(vf[4 * d0], vf[4 * d0 + 1]), o[d0], 0, 0, 0);
;         o[d0] = __builtin_amdgcn_mfma_f32_32x32x16_bf16(pa1, ATT_PK(vf[4 * d0 + 2], vf[4 * d0 + 3]), o[d0], 0, 0, 0); }
;     ...
; }
; template <int DQK, int D0A, int D0B> DI void k_reads(bf16x8* kf, const LAS unsigned char* Ks, int half, int r32, int hi) {
; #pragma unroll
;     for (int d0 = D0A; d0 < D0B; ++d0) kf[d0 - D0A] = *(const LAS bf16x8*)(Ks + half * (32 * DQK * 2) + kswz<DQK>(r32, (d0 * 16 + hi * 8) * 2));
; }
; template <int D0A, int D0B> DI void qk_mma(f32x16& p, const bf16x8* kf, const bf16x8* qr) {
; #pragma unroll
;     for (int d0 = D0A; d0 < D0B; ++d0) {
	v_mfma_f32_32x32x16_bf16 v[64:79], v[132:135], v[80:83], 0
	v_mfma_f32_32x32x16_bf16 v[64:79], v[136:139], v[84:87], v[64:79]
	v_mfma_f32_32x32x16_bf16 v[64:79], v[140:143], v[88:91], v[64:79]
	v_mfma_f32_32x32x16_bf16 v[64:79], v[174:177], v[92:95], v[64:79]
	v_mfma_f32_32x32x16_bf16 v[64:79], v[178:181], v[96:99], v[64:79]
	v_mfma_f32_32x32x16_bf16 v[64:79], v[182:185], v[100:103], v[64:79]
	s_waitcnt lgkmcnt(0)
	v_mfma_f32_32x32x16_bf16 v[64:79], v[218:221], v[104:107], v[64:79]
	v_mfma_f32_32x32x16_bf16 v[64:79], v[222:225], v[108:111], v[64:79]
	v_mfma_f32_32x32x16_bf16 v[64:79], v[226:229], v[112:115], v[64:79]
	v_mfma_f32_32x32x16_bf16 v[64:79], v[230:233], v[116:119], v[64:79]
	v_mfma_f32_32x32x16_bf16 v[64:79], v[234:237], v[120:123], v[64:79]
	v_mfma_f32_32x32x16_bf16 v[64:79], v[238:241], v[124:127], v[64:79]
	s_setprio 0
	ds_read_b128 v[132:135], v161 offset:49152
	ds_read_b128 v[136:139], v162 offset:49152
	ds_read_b128 v[140:143], v163 offset:49152
	ds_read_b128 v[174:177], v164 offset:49152
	ds_read_b128 v[178:181], v165 offset:49152
	ds_read_b128 v[182:185], v166 offset:49152
	ds_read_b64_tr_b16 v[186:187], v144 offset:0x2000
	ds_read_b64_tr_b16 v[188:189], v144 offset:0x2800
	ds_read_b64_tr_b16 v[190:191], v144 offset:0x3000
	ds_read_b64_tr_b16 v[192:193], v144 offset:0x3800
	ds_read_b64_tr_b16 v[194:195], v144 offset:0x2200
	ds_read_b64_tr_b16 v[196:197], v144 offset:0x2a00
	ds_read_b64_tr_b16 v[198:199], v144 offset:0x3200
	ds_read_b64_tr_b16 v[200:201], v144 offset:0x3a00
	ds_read_b64_tr_b16 v[202:203], v144 offset:0x2400
	ds_read_b64_tr_b16 v[204:205], v144 offset:0x2c00
	ds_read_b64_tr_b16 v[206:207], v144 offset:0x3400
	ds_read_b64_tr_b16 v[208:209], v144 offset:0x3c00
	ds_read_b64_tr_b16 v[210:211], v144 offset:0x2600
	ds_read_b64_tr_b16 v[212:213], v144 offset:0x2e00
	ds_read_b64_tr_b16 v[214:215], v144 offset:0x3600
	ds_read_b64_tr_b16 v[216:217], v144 offset:0x3e00
	s_nop 5
	s_setprio 2
	v_exp_f32_e32 v64, v64
	v_exp_f32_e32 v65, v65
	v_exp_f32_e32 v66, v66
	v_exp_f32_e32 v67, v67
	v_exp_f32_e32 v68, v68
	v_add_f32_e32 v144, 0, v64
	v_exp_f32_e32 v69, v69
	v_add_f32_e32 v144, v65, v144
	v_exp_f32_e32 v70, v70
	v_add_f32_e32 v144, v66, v144
	v_exp_f32_e32 v71, v71
	v_add_f32_e32 v144, v67, v144
	v_exp_f32_e32 v72, v72
	v_add_f32_e32 v144, v68, v144
	v_exp_f32_e32 v73, v73
	v_add_f32_e32 v144, v69, v144
	v_exp_f32_e32 v74, v74
	v_add_f32_e32 v144, v70, v144
	v_exp_f32_e32 v75, v75
	v_add_f32_e32 v144, v71, v144
	v_exp_f32_e32 v76, v76
	v_add_f32_e32 v144, v72, v144
	v_exp_f32_e32 v77, v77
	v_add_f32_e32 v144, v73, v144
	v_exp_f32_e32 v78, v78
	v_add_f32_e32 v144, v74, v144
	v_exp_f32_e32 v79, v79
	v_add_f32_e32 v144, v75, v144
	v_add_f32_e32 v144, v76, v144
	v_add_f32_e32 v144, v77, v144
	v_add_f32_e32 v144, v78, v144
	v_add_f32_e32 v144, v79, v144
	v_add_f32_e32 v144, v145, v144
	v_cvt_pk_bf16_f32 v64, v64, v65
	v_cvt_pk_bf16_f32 v65, v66, v67
	v_cvt_pk_bf16_f32 v66, v68, v69
	v_cvt_pk_bf16_f32 v67, v70, v71
	v_cvt_pk_bf16_f32 v68, v72, v73
	v_cvt_pk_bf16_f32 v69, v74, v75
	v_cvt_pk_bf16_f32 v70, v76, v77
	v_cvt_pk_bf16_f32 v71, v78, v79
	s_nop 0
	v_permlane32_swap_b32_e32 v64, v66
	v_permlane32_swap_b32_e32 v65, v67
	v_permlane32_swap_b32_e32 v68, v70
	v_permlane32_swap_b32_e32 v69, v71
	s_waitcnt lgkmcnt(0)
	ds_read_b128 v[218:221], v167 offset:49152
	ds_read_b128 v[222:225], v168 offset:49152
	ds_read_b128 v[226:229], v169 offset:49152
	ds_read_b128 v[230:233], v170 offset:49152
	ds_read_b128 v[234:237], v171 offset:49152
	ds_read_b128 v[238:241], v172 offset:49152
	s_setprio 1
	s_cmp_lt_u32 s33, 0x100
	s_cbranch_scc1 .Lstg_mla_m61_5
	s_waitcnt vmcnt(0)
	s_barrier
	s_setprio 2

; #define LAS __attribute__((address_space(3)))
; DI void expsum(f32x16& p, float& l_reg, bf16x8& pa0, bf16x8& pa1) {
; #pragma unroll
;     for (int r = 0; r < 16; ++r) p[r] = __builtin_amdgcn_exp2f(p[r]);
;     float ps = 0.f;
; #pragma unroll
;     for (int r = 0; r < 16; ++r) ps += p[r];
;     l_reg += ps; asm volatile("" : "+v"(l_reg));
;     ...
;     ATT_PK4(p, 0, pa0); ATT_PK4(p, 8, pa1);
;     ...
; }
; DI int v_rd_base(int lane) { return ((lane & 3) << 3) | (((lane >> 2) & 3) << 6) | (((lane >> 4) & 1) << 5) | (((lane >> 5) & 1) << 8); }
; template <int OFF> DI s16x4 tr_read(int vb) { s16x4 r; asm volatile("ds_read_b64_tr_b16 %0, %1 offset:%2" : "=&v"(r) : "v"(vb), "i"(OFF) : "memory"); return r; }
; template <int H> DI void v_reads(s16x4* vf, int vb) {
;     vf[0] = tr_read<v_rd_off(0, 2 * H, 0)>(vb); vf[1] = tr_read<v_rd_off(0, 2 * H, 1)>(vb); vf[2] = tr_read<v_rd_off(0, 2 * H + 1, 0)>(vb); vf[3] = tr_read<v_rd_off(0, 2 * H + 1, 1)>(vb);
;     vf[4] = tr_read<v_rd_off(1, 2 * H, 0)>(vb); vf[5] = tr_read<v_rd_off(1, 2 * H, 1)>(vb); vf[6] = tr_read<v_rd_off(1, 2 * H + 1, 0)>(vb); vf[7] = tr_read<v_rd_off(1, 2 * H + 1, 1)>(vb);
;     vf[8] = tr_read<v_rd_off(2, 2 * H, 0)>(vb); vf[9] = tr_read<v_rd_off(2, 2 * H, 1)>(vb); vf[10] = tr_read<v_rd_off(2, 2 * H + 1, 0)>(vb); vf[11] = tr_read<v_rd_off(2, 2 * H + 1, 1)>(vb);
;     vf[12] = tr_read<v_rd_off(3, 2 * H, 0)>(vb); vf[13] = tr_read<v_rd_off(3, 2 * H, 1)>(vb); vf[14] = tr_read<v_rd_off(3, 2 * H + 1, 0)>(vb); vf[15] = tr_read<v_rd_off(3, 2 * H + 1, 1)>(vb);
; }
; DI void pv_mma(f32x16* o, const s16x4* vf, bf16x8 pa0, bf16x8 pa1) {
;     ...
; #pragma unroll
;     for (int d0 = 0; d0 < 4; ++d0) {
;         o[d0] = __builtin_amdgcn_mfma_f32_32x32x16_bf16(pa0, ATT_PK(vf[4 * d0], vf[4 * d0 + 1]), o[d0], 0, 0, 0);
;         o[d0] = __builtin_amdgcn_mfma_f32_32x32x16_bf16(pa1, ATT_PK(vf[4 * d0 + 2], vf[4 * d0 + 3]), o[d0], 0, 0, 0); }
;     ...
; }
; template <int DQK, int D0A, int D0B> DI void k_reads(bf16x8* kf, const LAS unsigned char* Ks, int half, int r32, int hi) {
; #pragma unroll
;     for (int d0 = D0A; d0 < D0B; ++d0) kf[d0 - D0A] = *(const LAS bf16x8*)(Ks + half * (32 * DQK * 2) + kswz<DQK>(r32, (d0 * 16 + hi * 8) * 2));
; }
; template <int D0A, int D0B> DI void qk_mma(f32x16& p, const bf16x8* kf, const bf16x8* qr) {
; #pragma unroll
;     for (int d0 = D0A; d0 < D0B; ++d0) {
.Lstg_mla_t62_6:
	s_setprio 0
	ds_read_b128 v[132:135], v161 offset:61440
	ds_read_b128 v[136:139], v162 offset:61440
	ds_read_b128 v[140:143], v163 offset:61440
	ds_read_b128 v[174:177], v164 offset:61440
	ds_read_b128 v[162:165], v165 offset:61440
	ds_read_b128 v[178:181], v166 offset:61440
	v_add_u32_e32 v145, 0x8000, v130
	ds_read_b64_tr_b16 v[182:183], v145 offset:0
	ds_read_b64_tr_b16 v[184:185], v145 offset:0x800
	ds_read_b64_tr_b16 v[186:187], v145 offset:0x1000
	ds_read_b64_tr_b16 v[188:189], v145 offset:0x1800
	ds_read_b64_tr_b16 v[190:191], v145 offset:0x200
	ds_read_b64_tr_b16 v[192:193], v145 offset:0xa00
	ds_read_b64_tr_b16 v[194:195], v145 offset:0x1200
	ds_read_b64_tr_b16 v[196:197], v145 offset:0x1a00
	ds_read_b64_tr_b16 v[198:199], v145 offset:0x400
	ds_read_b64_tr_b16 v[200:201], v145 offset:0xc00
	ds_read_b64_tr_b16 v[202:203], v145 offset:0x1400
	ds_read_b64_tr_b16 v[204:205], v145 offset:0x1c00
	ds_read_b64_tr_b16 v[206:207], v145 offset:0x600
	ds_read_b64_tr_b16 v[208:209], v145 offset:0xe00
	ds_read_b64_tr_b16 v[210:211], v145 offset:0x1600
	ds_read_b64_tr_b16 v[212:213], v145 offset:0x1e00
	s_nop 3
	s_setprio 2
	v_exp_f32_e32 v64, v64
	v_exp_f32_e32 v65, v65
	v_exp_f32_e32 v66, v66
	v_exp_f32_e32 v67, v67
	v_exp_f32_e32 v68, v68
	v_add_f32_e32 v161, 0, v64
	v_exp_f32_e32 v69, v69
	v_add_f32_e32 v161, v65, v161
	v_exp_f32_e32 v70, v70
	v_add_f32_e32 v161, v66, v161
	v_exp_f32_e32 v71, v71
	v_add_f32_e32 v161, v67, v161
	v_exp_f32_e32 v72, v72
	v_add_f32_e32 v161, v68, v161
	v_exp_f32_e32 v73, v73
	v_add_f32_e32 v161, v69, v161
	v_exp_f32_e32 v74, v74
	v_add_f32_e32 v161, v70, v161
	v_exp_f32_e32 v75, v75
	v_add_f32_e32 v161, v71, v161
	v_exp_f32_e32 v76, v76
	v_add_f32_e32 v161, v72, v161
	v_exp_f32_e32 v77, v77
	v_add_f32_e32 v161, v73, v161
	v_exp_f32_e32 v78, v78
	v_add_f32_e32 v161, v74, v161
	v_exp_f32_e32 v79, v79
	v_add_f32_e32 v161, v75, v161
	v_add_f32_e32 v161, v76, v161
	v_add_f32_e32 v161, v77, v161
	v_add_f32_e32 v161, v78, v161
	v_add_f32_e32 v161, v79, v161
	v_add_f32_e32 v144, v144, v161
	v_cvt_pk_bf16_f32 v64, v64, v65
	v_cvt_pk_bf16_f32 v65, v66, v67
	v_cvt_pk_bf16_f32 v66, v68, v69
	v_cvt_pk_bf16_f32 v67, v70, v71
	v_cvt_pk_bf16_f32 v68, v72, v73
	v_cvt_pk_bf16_f32 v69, v74, v75
	v_cvt_pk_bf16_f32 v70, v76, v77
	v_cvt_pk_bf16_f32 v71, v78, v79
	s_nop 0
	v_permlane32_swap_b32_e32 v64, v66
	v_permlane32_swap_b32_e32 v65, v67
	v_permlane32_swap_b32_e32 v68, v70
	v_permlane32_swap_b32_e32 v69, v71
	s_waitcnt lgkmcnt(0)
	ds_read_b128 v[214:217], v167 offset:61440
	ds_read_b128 v[218:221], v168 offset:61440
	ds_read_b128 v[166:169], v169 offset:61440
	ds_read_b128 v[222:225], v170 offset:61440
	ds_read_b128 v[226:229], v171 offset:61440
	ds_read_b128 v[170:173], v172 offset:61440
	s_setprio 1
	v_mfma_f32_32x32x16_bf16 v[48:63], v[64:67], v[182:185], v[48:63]
	v_mfma_f32_32x32x16_bf16 v[32:47], v[64:67], v[190:193], v[32:47]
	v_mfma_f32_32x32x16_bf16 v[16:31], v[64:67], v[198:201], v[16:31]
	v_mfma_f32_32x32x16_bf16 v[0:15], v[64:67], v[206:209], v[0:15]
	v_mfma_f32_32x32x16_bf16 v[48:63], v[68:71], v[186:189], v[48:63]
	v_mfma_f32_32x32x16_bf16 v[32:47], v[68:71], v[194:197], v[32:47]
	v_mfma_f32_32x32x16_bf16 v[16:31], v[68:71], v[202:205], v[16:31]
	v_mfma_f32_32x32x16_bf16 v[0:15], v[68:71], v[210:213], v[0:15]
	s_waitcnt lgkmcnt(0)
	v_mfma_f32_32x32x16_bf16 v[64:79], v[132:135], v[80:83], 0
	v_mfma_f32_32x32x16_bf16 v[64:79], v[136:139], v[84:87], v[64:79]
	v_mfma_f32_32x32x16_bf16 v[64:79], v[140:143], v[88:91], v[64:79]
	v_mfma_f32_32x32x16_bf16 v[64:79], v[174:177], v[92:95], v[64:79]
	v_mfma_f32_32x32x16_bf16 v[64:79], v[162:165], v[96:99], v[64:79]
	v_mfma_f32_32x32x16_bf16 v[64:79], v[178:181], v[100:103], v[64:79]
	s_waitcnt lgkmcnt(0)
; #define LAS __attribute__((address_space(3)))
; DI void expsum(f32x16& p, float& l_reg, bf16x8& pa0, bf16x8& pa1) {
; #pragma unroll
;     for (int r = 0; r < 16; ++r) p[r] = __builtin_amdgcn_exp2f(p[r]);
;     float ps = 0.f;
; #pragma unroll
;     for (int r = 0; r < 16; ++r) ps += p[r];
;     l_reg += ps; asm volatile("" : "+v"(l_reg));
;     ...
;     ATT_PK4(p, 0, pa0); ATT_PK4(p, 8, pa1);
;     ...
; }
; DI int v_rd_base(int lane) { return ((lane & 3) << 3) | (((lane >> 2) & 3) << 6) | (((lane >> 4) & 1) << 5) | (((lane >> 5) & 1) << 8); }
; template <int OFF> DI s16x4 tr_read(int vb) { s16x4 r; asm volatile("ds_read_b64_tr_b16 %0, %1 offset:%2" : "=&v"(r) : "v"(vb), "i"(OFF) : "memory"); return r; }
; template <int H> DI void v_reads(s16x4* vf, int vb) {
;     vf[0] = tr_read<v_rd_off(0, 2 * H, 0)>(vb); vf[1] = tr_read<v_rd_off(0, 2 * H, 1)>(vb); vf[2] = tr_read<v_rd_off(0, 2 * H + 1, 0)>(vb); vf[3] = tr_read<v_rd_off(0, 2 * H + 1, 1)>(vb);
;     vf[4] = tr_read<v_rd_off(1, 2 * H, 0)>(vb); vf[5] = tr_read<v_rd_off(1, 2 * H, 1)>(vb); vf[6] = tr_read<v_rd_off(1, 2 * H + 1, 0)>(vb); vf[7] = tr_read<v_rd_off(1, 2 * H + 1, 1)>(vb);
;     vf[8] = tr_read<v_rd_off(2, 2 * H, 0)>(vb); vf[9] = tr_read<v_rd_off(2, 2 * H, 1)>(vb); vf[10] = tr_read<v_rd_off(2, 2 * H + 1, 0)>(vb); vf[11] = tr_read<v_rd_off(2, 2 * H + 1, 1)>(vb);
;     vf[12] = tr_read<v_rd_off(3, 2 * H, 0)>(vb); vf[13] = tr_read<v_rd_off(3, 2 * H, 1)>(vb); vf[14] = tr_read<v_rd_off(3, 2 * H + 1, 0)>(vb); vf[15] = tr_read<v_rd_off(3, 2 * H + 1, 1)>(vb);
; }
; DI void pv_mma(f32x16* o, const s16x4* vf, bf16x8 pa0, bf16x8 pa1) {
;     ...
; #pragma unroll
;     for (int d0 = 0; d0 < 4; ++d0) {
;         o[d0] = __builtin_amdgcn_mfma_f32_32x32x16_bf16(pa0, ATT_PK(vf[4 * d0], vf[4 * d0 + 1]), o[d0], 0, 0, 0);
;         o[d0] = __builtin_amdgcn_mfma_f32_32x32x16_bf16(pa1, ATT_PK(vf[4 * d0 + 2], vf[4 * d0 + 3]), o[d0], 0, 0, 0); }
;     ...
; }
; template <int DQK, int D0A, int D0B> DI void k_reads(bf16x8* kf, const LAS unsigned char* Ks, int half, int r32, int hi) {
; #pragma unroll
;     for (int d0 = D0A; d0 < D0B; ++d0) kf[d0 - D0A] = *(const LAS bf16x8*)(Ks + half * (32 * DQK * 2) + kswz<DQK>(r32, (d0 * 16 + hi * 8) * 2));
; }
; template <int D0A, int D0B> DI void qk_mma(f32x16& p, const bf16x8* kf, const bf16x8* qr) {
; #pragma unroll
;     for (int d0 = D0A; d0 < D0B; ++d0) {
	v_mfma_f32_32x32x16_bf16 v[64:79], v[214:217], v[104:107], v[64:79]
	v_mfma_f32_32x32x16_bf16 v[64:79], v[218:221], v[108:111], v[64:79]
	v_mfma_f32_32x32x16_bf16 v[64:79], v[166:169], v[112:115], v[64:79]
	v_mfma_f32_32x32x16_bf16 v[64:79], v[222:225], v[116:119], v[64:79]
	v_mfma_f32_32x32x16_bf16 v[64:79], v[226:229], v[120:123], v[64:79]
	v_mfma_f32_32x32x16_bf16 v[64:79], v[170:173], v[124:127], v[64:79]
	s_setprio 0
	v_add_u32_e32 v158, 0x12000, v158
	v_add_u32_e32 v132, v158, v151
	v_add_u32_e32 v136, v158, v149
	v_add_u32_e32 v140, v158, v148
	v_add_u32_e32 v161, v158, v147
	ds_read_b128 v[132:135], v132
	ds_read_b128 v[136:139], v136
	ds_read_b128 v[140:143], v140
	ds_read_b128 v[162:165], v161
	v_add_u32_e32 v161, v158, v146
	v_add_u32_e32 v170, v158, v150
	ds_read_b128 v[166:169], v161
	ds_read_b128 v[170:173], v170
	ds_read_b64_tr_b16 v[174:175], v145 offset:0x2000
	ds_read_b64_tr_b16 v[176:177], v145 offset:0x2800
	ds_read_b64_tr_b16 v[178:179], v145 offset:0x3000
	ds_read_b64_tr_b16 v[180:181], v145 offset:0x3800
	ds_read_b64_tr_b16 v[182:183], v145 offset:0x2200
	ds_read_b64_tr_b16 v[184:185], v145 offset:0x2a00
	ds_read_b64_tr_b16 v[186:187], v145 offset:0x3200
	ds_read_b64_tr_b16 v[188:189], v145 offset:0x3a00
	ds_read_b64_tr_b16 v[190:191], v145 offset:0x2400
	ds_read_b64_tr_b16 v[192:193], v145 offset:0x2c00
	ds_read_b64_tr_b16 v[194:195], v145 offset:0x3400
	ds_read_b64_tr_b16 v[196:197], v145 offset:0x3c00
	ds_read_b64_tr_b16 v[198:199], v145 offset:0x2600
	ds_read_b64_tr_b16 v[200:201], v145 offset:0x2e00
	ds_read_b64_tr_b16 v[202:203], v145 offset:0x3600
	ds_read_b64_tr_b16 v[204:205], v145 offset:0x3e00
	s_setprio 2
	v_exp_f32_e32 v64, v64
	v_exp_f32_e32 v65, v65
	v_exp_f32_e32 v66, v66
	v_exp_f32_e32 v67, v67
	v_exp_f32_e32 v68, v68
	v_add_f32_e32 v145, 0, v64
	v_exp_f32_e32 v69, v69
	v_add_f32_e32 v145, v65, v145
	v_exp_f32_e32 v70, v70
	v_add_f32_e32 v145, v66, v145
	v_exp_f32_e32 v71, v71
	v_add_f32_e32 v145, v67, v145
	v_exp_f32_e32 v72, v72
	v_add_f32_e32 v145, v68, v145
	v_exp_f32_e32 v73, v73
	v_add_f32_e32 v145, v69, v145
	v_exp_f32_e32 v74, v74
	v_add_f32_e32 v145, v70, v145
	v_exp_f32_e32 v75, v75
	v_add_f32_e32 v145, v71, v145
	v_exp_f32_e32 v76, v76
	v_add_f32_e32 v145, v72, v145
	v_exp_f32_e32 v77, v77
	v_add_f32_e32 v145, v73, v145
	v_exp_f32_e32 v78, v78
	v_add_f32_e32 v145, v74, v145
	v_exp_f32_e32 v79, v79
	v_add_f32_e32 v145, v75, v145
	v_add_f32_e32 v145, v76, v145
	v_add_f32_e32 v145, v77, v145
	v_add_f32_e32 v145, v78, v145
	v_add_f32_e32 v145, v79, v145
	v_add_f32_e32 v161, v144, v145
	v_cvt_pk_bf16_f32 v64, v64, v65
	v_cvt_pk_bf16_f32 v65, v66, v67
	v_cvt_pk_bf16_f32 v66, v68, v69
	v_cvt_pk_bf16_f32 v67, v70, v71
	v_cvt_pk_bf16_f32 v68, v72, v73
	v_cvt_pk_bf16_f32 v69, v74, v75
	v_cvt_pk_bf16_f32 v70, v76, v77
	v_cvt_pk_bf16_f32 v71, v78, v79
	s_nop 0
	v_permlane32_swap_b32_e32 v64, v66
	v_permlane32_swap_b32_e32 v65, v67
	v_permlane32_swap_b32_e32 v68, v70
	v_permlane32_swap_b32_e32 v69, v71
	s_waitcnt lgkmcnt(0)
	v_add_u32_e32 v72, v158, v152
	v_add_u32_e32 v73, v158, v153
	ds_read_b128 v[206:209], v72
	ds_read_b128 v[210:213], v73
	v_add_u32_e32 v72, v158, v154
	v_add_u32_e32 v73, v158, v155
	ds_read_b128 v[214:217], v72
	ds_read_b128 v[218:221], v73
	v_add_u32_e32 v72, v158, v156
	v_add_u32_e32 v73, v158, v157
	ds_read_b128 v[222:225], v72
	ds_read_b128 v[226:229], v73
	s_setprio 1
	s_cmp_lt_u32 s33, 0x100
	s_cbranch_scc1 .Lstg_mla_m62_7
	s_waitcnt vmcnt(0)
	s_barrier
	s_setprio 2
